# E1 + batch-0 attention q/k norm+rotary moved from the rope phase into batch 0's selection phase (waves 4-7 before, waves 0-3 after their rows)
# speedup vs baseline: 1.0329x; 1.0105x over previous
; __device__ __forceinline__ void post_proj(const Args& A, int gw, int NGW, int lane) {
;     unsigned char* ws = A.ws;
;     const float* R1 = (const float*)(ws + WS_ROPE1); const float* R2 = (const float*)(ws + WS_ROPE2);
;     const float qs = 0.08838834764831845f;
;     rope_pass<true, 128, true>((bf16_t*)(ws + WS_DQ), T * 4, A.q_norm_g, R1, qs * 1.4426950408889634f  , gw, NGW, lane);
;     rope_pass<true, 128, false>((bf16_t*)(ws + WS_DK), T, A.k_norm_g, R1, 1.f, gw, NGW, lane);
;     rope_pass<false, 64, true>((bf16_t*)(ws + WS_IQ), T * 4, nullptr, R2, qs, gw, NGW, lane);
;     rope_pass<true, 64, false>((bf16_t*)(ws + WS_IK), T / 4, A.idx_k_norm_g, R2, 1.f, gw, NGW, lane);
; }
.LBB0_1068:
	s_cmp_lt_i32 s42, 3
	s_cselect_b64 s[8:9], -1, 0
	s_and_b64 s[0:1], s[8:9], s[4:5]
	s_andn2_b64 vcc, exec, s[0:1]
	s_cbranch_vccnz .LBB0_1081
	v_readlane_b32 s0, v255, 0
	v_readlane_b32 s1, v255, 1
	s_load_dwordx2 s[10:11], s[0:1], 0x88
	s_load_dwordx4 s[4:7], s[0:1], 0x38
	s_load_dwordx2 s[12:13], s[0:1], 0x48
	s_lshl_b32 s0, s2, 3
	v_readlane_b32 s1, v255, 3
	s_add_i32 s0, s1, s0
	s_waitcnt lgkmcnt(0)
	s_add_u32 s16, s10, 0x400000
	s_addc_u32 s17, s11, 0
	s_cmpk_lt_i32 s0, 0x2000
	v_mbcnt_lo_u32_b32 v179, -1, 0
	v_mbcnt_hi_u32_b32 v179, -1, v179
	s_cselect_b64 s[14:15], -1, 0
	s_cmpk_gt_i32 s0, 0x1fff
	v_lshlrev_b32_e32 v156, 3, v179
	v_lshlrev_b32_e32 v180, 6, v179
	v_lshlrev_b32_e32 v124, 5, v179
	v_and_b32_e32 v181, 8, v179
	s_branch .LBB0_1072
.LBB0_1072:
	s_cmpk_gt_i32 s0, 0x3ff
	v_ashrrev_i32_e32 v178, 4, v179
	s_branch .LBB0_1075

; #define LAS __attribute__((address_space(3)))
; __device__ __forceinline__ void select_one(const unsigned short* sc, int t, unsigned short* idx, int lane, LAS unsigned short* li, LAS unsigned* hist) {
;     if (t < 256) {
; #pragma unroll
;         for (int j = 0; j < 4; ++j) { const int i = j * 64 + lane; idx[i] = (unsigned short)(i <= t ? i : 0); }
;         return;
;     }
;     unsigned key[128];
;     const int ngrp = (t >> 9) + 1;
;     u32x4 wv[16];
; #pragma unroll
;     for (int gI = 0; gI < 16; ++gI) wv[gI] = *(const u32x4*)(sc + gI * 512 + lane * 8);
; #pragma unroll
;     for (int gI = 0; gI < 16; ++gI) {
;         const int s0 = gI * 512 + lane * 8; const u32x4 w = wv[gI];
; #pragma unroll
;         for (int q = 0; q < 8; ++q) { const unsigned wd = w[q >> 1]; const unsigned h = (q & 1) ? (wd >> 16) : (wd & 0xffffu);
;             const unsigned k = (h & 0x8000u) ? (~h & 0xffffu) : (h | 0x8000u); key[gI * 8 + q] = (s0 + q <= t) ? k : 0u; }
;     }
.LBB0_1209:
	s_cmp_lt_i32 s42, 5
	s_cselect_b64 s[50:51], -1, 0
	s_and_b64 s[0:1], s[50:51], s[6:7]
	s_andn2_b64 vcc, exec, s[0:1]
	s_cbranch_vccnz .LBB0_2875
	v_readlane_b32 s91, v255, 3
	s_cmp_gt_u32 s91, 3
	s_cbranch_scc1 .Lrope_a0
.Lsel_a_go:
	v_readlane_b32 s0, v255, 0
	v_readlane_b32 s1, v255, 1
	s_lshl_b32 s0, s2, 3
	v_readlane_b32 s1, v255, 3
	s_add_i32 s52, s1, s0
	s_cmpk_gt_i32 s52, 0x1fff
	s_waitcnt vmcnt(0)
	v_mbcnt_lo_u32_b32 v68, -1, 0
	v_mbcnt_hi_u32_b32 v68, -1, v68
	s_cbranch_scc1 .LBB0_2875
	s_add_u32 s0, s40, 0xe00000
	v_readlane_b32 s3, v255, 3
	s_addc_u32 s1, s41, 0
	s_lshl_b32 s4, s3, 9
	v_lshlrev_b32_e32 v70, 3, v68
	s_add_i32 s3, s4, 0
	v_ashrrev_i32_e32 v71, 31, v70
	s_add_i32 s6, s3, s4
	v_lshl_add_u64 v[0:1], v[70:71], 1, s[40:41]
	s_mov_b64 s[4:5], 0x17800000
	v_lshl_add_u64 v[72:73], v[0:1], 0, s[4:5]
	v_lshlrev_b32_e32 v1, 4, v68
	v_lshlrev_b32_e32 v74, 2, v68
	v_mov_b32_e32 v0, 0
	s_add_i32 s33, s6, 0x1000
	v_or_b32_e32 v71, 2, v70
	v_or_b32_e32 v76, 3, v70
	v_or_b32_e32 v77, 4, v70
	v_or_b32_e32 v78, 5, v70
	v_or_b32_e32 v79, 6, v70
	v_or_b32_e32 v80, 7, v70
	v_add_u32_e32 v101, 0x604, v70
	v_add_u32_e32 v102, 0x605, v70
	v_add_u32_e32 v103, 0x606, v70
	v_add_u32_e32 v104, 0x607, v70
	v_add_u32_e32 v105, 0x800, v70
	v_add_u32_e32 v106, 0x801, v70
	v_add_u32_e32 v107, 0x802, v70
	v_add_u32_e32 v108, 0x803, v70
	v_add_u32_e32 v109, 0x804, v70
	v_add_u32_e32 v110, 0x805, v70
	v_add_u32_e32 v111, 0x806, v70
	v_add_u32_e32 v112, 0x807, v70
	v_add_u32_e32 v113, 0xa00, v70
	v_add_u32_e32 v114, 0xa01, v70
	v_add_u32_e32 v115, 0xa02, v70
	v_add_u32_e32 v116, 0xa03, v70
	v_add_u32_e32 v117, 0xa04, v70
	v_add_u32_e32 v118, 0xa05, v70
	v_add_u32_e32 v119, 0xa06, v70
	v_add_u32_e32 v120, 0xa07, v70
	v_add_u32_e32 v121, 0xc00, v70
	v_add_u32_e32 v122, 0xc01, v70
	v_add_u32_e32 v123, 0xc02, v70
	v_add_u32_e32 v124, 0xc03, v70
	v_add_u32_e32 v125, 0xc04, v70
	v_add_u32_e32 v126, 0xc05, v70
	v_add_u32_e32 v127, 0xc06, v70
	v_add_u32_e32 v128, 0xc07, v70
	v_add_u32_e32 v129, 0xe00, v70
	v_add_u32_e32 v130, 0xe01, v70
	v_add_u32_e32 v131, 0xe02, v70
	v_add_u32_e32 v132, 0xe03, v70
	v_add_u32_e32 v133, 0xe04, v70
	v_add_u32_e32 v134, 0xe05, v70
	v_add_u32_e32 v135, 0xe06, v70
	v_add_u32_e32 v136, 0xe07, v70
	v_add_u32_e32 v137, 0x1000, v70
	v_add_u32_e32 v138, 0x1001, v70
	v_add_u32_e32 v139, 0x1002, v70
	v_add_u32_e32 v140, 0x1003, v70
	v_add_u32_e32 v141, 0x1004, v70
	v_add_u32_e32 v142, 0x1005, v70
	v_add_u32_e32 v143, 0x1006, v70
	v_add_u32_e32 v144, 0x1007, v70
	v_add_u32_e32 v145, 0x1200, v70
	v_add_u32_e32 v146, 0x1201, v70
	v_add_u32_e32 v147, 0x1202, v70
	v_add_u32_e32 v148, 0x1203, v70
	v_add_u32_e32 v149, 0x1204, v70
	v_add_u32_e32 v150, 0x1205, v70
	v_add_u32_e32 v151, 0x1206, v70
	v_add_u32_e32 v152, 0x1207, v70
	v_add_u32_e32 v153, 0x1400, v70
	v_add_u32_e32 v154, 0x1401, v70
	v_add_u32_e32 v155, 0x1402, v70
	v_add_u32_e32 v156, 0x1403, v70
	v_add_u32_e32 v157, 0x1404, v70
	v_add_u32_e32 v158, 0x1405, v70
	v_add_u32_e32 v159, 0x1406, v70
	v_add_u32_e32 v160, 0x1407, v70
	v_add_u32_e32 v161, 0x1600, v70
	v_add_u32_e32 v162, 0x1601, v70
	v_add_u32_e32 v163, 0x1602, v70
	v_add_u32_e32 v164, 0x1603, v70
	v_add_u32_e32 v165, 0x1604, v70
	v_add_u32_e32 v166, 0x1605, v70
	v_add_u32_e32 v167, 0x1606, v70
	v_add_u32_e32 v168, 0x1607, v70
	v_add_u32_e32 v169, 0x1800, v70
	v_add_u32_e32 v170, 0x1801, v70
	v_add_u32_e32 v171, 0x1802, v70
	v_add_u32_e32 v172, 0x1803, v70
	v_add_u32_e32 v173, 0x1804, v70
	v_add_u32_e32 v174, 0x1805, v70
	v_add_u32_e32 v175, 0x1806, v70
	v_add_u32_e32 v176, 0x1807, v70
	v_add_u32_e32 v177, 0x1a00, v70
	v_add_u32_e32 v178, 0x1a01, v70
	v_add_u32_e32 v179, 0x1a02, v70
	v_add_u32_e32 v180, 0x1a03, v70
	v_add_u32_e32 v181, 0x1a04, v70
	v_add_u32_e32 v182, 0x1a05, v70
	v_add_u32_e32 v183, 0x1a06, v70
	v_add_u32_e32 v184, 0x1a07, v70
	v_add_u32_e32 v185, 0x1c00, v70
	v_add_u32_e32 v186, 0x1c01, v70
	v_add_u32_e32 v187, 0x1c02, v70
	v_add_u32_e32 v188, 0x1c03, v70
	v_add_u32_e32 v189, 0x1c04, v70
	v_add_u32_e32 v190, 0x1c05, v70
	v_add_u32_e32 v191, 0x1c06, v70
	v_add_u32_e32 v192, 0x1c07, v70
	v_add_u32_e32 v193, 0x1e00, v70
	v_add_u32_e32 v194, 0x1e01, v70
	v_add_u32_e32 v195, 0x1e02, v70
	v_add_u32_e32 v196, 0x1e03, v70
	v_add_u32_e32 v197, 0x1e04, v70
	v_add_u32_e32 v198, 0x1e05, v70
	v_add_u32_e32 v199, 0x1e06, v70
	v_add_u32_e32 v200, 0x1e07, v70
	v_ashrrev_i32_e32 v75, 31, v74
	v_ashrrev_i32_e32 v69, 31, v68
	v_add_u32_e32 v202, 64, v68
	v_add_u32_e32 v203, 0x80, v68
	v_add_u32_e32 v204, 0xc0, v68
	s_mov_b32 s45, 0xffff
	s_mov_b32 s46, 0x8000
	v_mov_b32_e32 v205, 1
	v_add_u32_e32 v206, s6, v1
	v_mov_b32_e32 v1, v0
	v_mov_b32_e32 v2, v0
	v_mov_b32_e32 v3, v0
	s_branch .LBB0_1213

; template <bool NORM, int ROT, bool PERTOK> __device__ __forceinline__ void rope_pass(bf16_t* base, int nchunks, const float* g, const float* tab, float sc, int gw, int NGW, int lane) {
;     constexpr int NB = 8, HALFL = ROT / 16; const int j = lane & 15;
;     for (int it0 = gw * NB; it0 < nchunks; it0 += NGW * NB) {
;         u32x4 w[NB]; f32x4 tb[NB][4];
; #pragma unroll
;         for (int k = 0; k < NB; ++k) { const int it = it0 + k;
;             w[k] = *(const u32x4*)(base + (size_t)it * 512 + lane * 8);
;             const int pos = PERTOK ? ((it >> 2) & 8191) : (((it * 4) & 8191) + (lane >> 4));
;             const float* tp = tab + (size_t)pos * ROT + (j & (HALFL - 1)) * 16;
; __device__ __forceinline__ void post_proj(const Args& A, int gw, int NGW, int lane) {
;     unsigned char* ws = A.ws;
;     const float* R1 = (const float*)(ws + WS_ROPE1); const float* R2 = (const float*)(ws + WS_ROPE2);
;     const float qs = 0.08838834764831845f;
;     rope_pass<true, 128, true>((bf16_t*)(ws + WS_DQ), T * 4, A.q_norm_g, R1, qs * 1.4426950408889634f  , gw, NGW, lane);
.Lsel_a_exit:
	v_readlane_b32 s91, v255, 3
	s_cmp_lt_u32 s91, 4
	s_cbranch_scc1 .Lrope_a0
	s_branch .LBB0_2874
.Lrope_a0:
	v_readlane_b32 s0, v255, 0
	v_readlane_b32 s1, v255, 1
	s_load_dwordx2 s[10:11], s[0:1], 0x88
	s_load_dwordx4 s[4:7], s[0:1], 0x38
	s_load_dwordx2 s[12:13], s[0:1], 0x48
	s_lshl_b32 s0, s2, 3
	v_readlane_b32 s1, v255, 3
	s_add_i32 s0, s1, s0
	s_waitcnt lgkmcnt(0)
	s_add_u32 s16, s10, 0x400000
	s_addc_u32 s17, s11, 0
	s_cmpk_lt_i32 s0, 0x2000
	v_mbcnt_lo_u32_b32 v179, -1, 0
	v_mbcnt_hi_u32_b32 v179, -1, v179
	s_cselect_b64 s[14:15], -1, 0
	s_cmpk_gt_i32 s0, 0x1fff
	v_lshlrev_b32_e32 v156, 3, v179
	v_lshlrev_b32_e32 v180, 6, v179
	v_lshlrev_b32_e32 v124, 5, v179
	v_and_b32_e32 v181, 8, v179
	s_cbranch_scc1 .Lra_1072
	s_lshl_b32 s18, s0, 3
	v_readlane_b32 s3, v255, 3
	s_lshl_b32 s1, s2, 11
	s_lshl_b32 s3, s3, 8
	s_ashr_i32 s19, s18, 31
	s_lshl_b32 s22, s44, 6
	s_add_i32 s1, s1, s3
	s_lshl_b32 s3, s44, 11
	s_lshl_b64 s[24:25], s[18:19], 10
	v_and_b32_e32 v0, 0x1c0, v180
	v_mov_b32_e32 v1, 0
	s_add_u32 s24, s10, s24
	v_ashrrev_i32_e32 v157, 31, v156
	v_lshl_add_u64 v[104:105], s[16:17], 0, v[0:1]
	v_and_b32_e32 v0, 0x1e0, v124
	s_addc_u32 s25, s11, s25
	v_lshl_add_u64 v[106:107], s[4:5], 0, v[0:1]
	v_lshl_add_u64 v[0:1], v[156:157], 1, s[24:25]
	s_mov_b64 s[24:25], 0xd801c00
	s_ashr_i32 s23, s22, 31
	s_mov_b32 s21, 0
	v_cmp_eq_u32_e64 s[4:5], 0, v181
	v_lshl_add_u64 v[108:109], v[0:1], 0, s[24:25]
	s_lshl_b64 s[24:25], s[22:23], 10
	s_movk_i32 s19, 0xe800
	s_movk_i32 s23, 0xec00
	s_movk_i32 s26, 0xf000
	s_movk_i32 s27, 0xf400
	s_movk_i32 s28, 0xf800
	s_movk_i32 s29, 0xfc00
	v_mov_b32_e32 v125, 0x358637bd
	s_mov_b32 s30, 0x800000
